# weight-prep channel-DFT fold moved from a VALU/LDS f32 fma chain (with exec-masked table select) to v_mfma_f32_16x16x4_f32 (f32 operands, f32 accumulate, same k-ordered chain); -sin table stored once,
# speedup vs baseline: 1.0060x; 1.0054x over previous
; __device__ __forceinline__ int opaque_tid() { int t = threadIdx.x; asm volatile("" : "+v"(t)); return t; }
; __device__ __forceinline__ u32x4 pack8(f32x4 a, f32x4 b) { u32x4 o; o[0] = cvt_pk_bf16(a[0], a[1]); o[1] = cvt_pk_bf16(a[2], a[3]); o[2] = cvt_pk_bf16(b[0], b[1]); o[3] = cvt_pk_bf16(b[2], b[3]); return o; }
; __device__ void prep_zfold(const float* __restrict__ wmix  , const float* __restrict__ gain, bf16_t* __restrict__ WM1, int& tbase, float* lt) {
;   const int tid = opaque_tid(), G = gridDim.x;
;   float* cosT = lt + 16 * 129; float* sinT = cosT + 128;
;   int start = (int)blockIdx.x - (tbase % G); if (start < 0) start += G;
;   for (int t = start; t < 256; t += G) {
;     const int grp = t >> 6, k0 = (t & 63) << 4;
;     { const int k = tid >> 5, c4 = tid & 31; const f32x4 v = *(const f32x4*)(wmix + (size_t)(k0 + k) * 5632 + grp * 128 + c4 * 4);
;       float* p = lt + k * 129 + c4 * 4; p[0] = v[0]; p[1] = v[1]; p[2] = v[2]; p[3] = v[3]; }
;     if (tid < 128) { cosT[tid] = __builtin_amdgcn_cosf((float)tid * (1.f / 128.f)); sinT[tid] = __builtin_amdgcn_sinf((float)tid * (1.f / 128.f)); }
;     __syncthreads();
;     { const int nl = tid >> 1, ri = nl >> 7, cc = nl & 127, kh = (tid & 1) << 3;
;       float a0 = 0.f, a1 = 0.f, a2 = 0.f, a3 = 0.f, a4 = 0.f, a5 = 0.f, a6 = 0.f, a7 = 0.f;
;       const float* lp = lt + kh * 129;
;       for (int c = 0; c < 128; ++c) {
;         const int idx = (c * cc) & 127; const float w = ri ? -sinT[idx] : cosT[idx];
;         a0 += lp[c] * w; a1 += lp[129 + c] * w; a2 += lp[2 * 129 + c] * w; a3 += lp[3 * 129 + c] * w;
;         a4 += lp[4 * 129 + c] * w; a5 += lp[5 * 129 + c] * w; a6 += lp[6 * 129 + c] * w; a7 += lp[7 * 129 + c] * w;
;       }
;       const float sc = 0.08838834764831845f; const float* gp = gain + k0 + kh;
;       f32x4 o0 = {a0 * sc * gp[0], a1 * sc * gp[1], a2 * sc * gp[2], a3 * sc * gp[3]}, o1 = {a4 * sc * gp[4], a5 * sc * gp[5], a6 * sc * gp[6], a7 * sc * gp[7]};
;       *(u32x4*)(WM1 + (size_t)(ri * 512 + grp * 128 + cc) * 1024 + k0 + kh) = pack8(o0, o1); }
;     __syncthreads();
.LBB0_56:
	v_readlane_b32 s60, v250, 0
	s_lshl_b64 s[38:39], s[20:21], 2
	v_readlane_b32 s74, v250, 14
	v_readlane_b32 s61, v250, 1
	v_readlane_b32 s62, v250, 2
	v_readlane_b32 s63, v250, 3
	v_readlane_b32 s64, v250, 4
	v_readlane_b32 s65, v250, 5
	v_readlane_b32 s66, v250, 6
	v_readlane_b32 s67, v250, 7
	v_readlane_b32 s68, v250, 8
	v_readlane_b32 s69, v250, 9
	v_readlane_b32 s70, v250, 10
	v_readlane_b32 s71, v250, 11
	v_readlane_b32 s72, v250, 12
	v_readlane_b32 s73, v250, 13
	v_readlane_b32 s75, v250, 15
	s_add_u32 s34, s74, s38
	s_addc_u32 s35, s75, s39
	s_lshl_b64 s[40:41], s[40:41], 2
	v_readlane_b32 s60, v250, 17
	v_readlane_b32 s6, v254, 23
	v_readlane_b32 s61, v250, 18
	s_add_u32 s42, s60, s40
	v_readlane_b32 s7, v254, 24
	s_addc_u32 s43, s61, s41
	v_mov_b32_e32 v2, v214
	s_andn2_b64 vcc, exec, s[6:7]
	v_readlane_b32 s62, v250, 19
	v_readlane_b32 s63, v250, 20
	v_readlane_b32 s64, v250, 21
	v_readlane_b32 s65, v250, 22
	v_readlane_b32 s66, v250, 23
	v_readlane_b32 s67, v250, 24
	v_readlane_b32 s68, v250, 25
	v_readlane_b32 s69, v250, 26
	v_readlane_b32 s70, v250, 27
	v_readlane_b32 s71, v250, 28
	v_readlane_b32 s72, v250, 29
	v_readlane_b32 s73, v250, 30
	v_readlane_b32 s74, v250, 31
	v_readlane_b32 s75, v250, 32
	s_cbranch_vccnz .LBB0_79
	v_cvt_f32_i32_e32 v5, v2
	v_lshlrev_b32_e32 v0, 2, v2
	v_ashrrev_i32_e32 v13, 5, v2
	v_and_b32_e32 v4, 0x7c, v0
	s_movk_i32 s7, 0x204
	v_mul_lo_u32 v1, v13, s7
	v_lshlrev_b32_e32 v3, 2, v4
	v_add3_u32 v15, 0, v1, v3
	v_add_u32_e32 v3, 0, v0
	v_mul_f32_e32 v0, 0x3c000000, v5
	s_movk_i32 s6, 0x80
	v_sin_f32_e32 v25, v0
	v_cos_f32_e32 v37, v0
	v_lshlrev_b32_e32 v0, 3, v2
	v_cmp_gt_i32_e32 vcc, s6, v2
	v_and_b32_e32 v6, 8, v0
	s_movk_i32 s6, 0xff
	v_lshrrev_b32_e32 v44, 1, v2
	v_bfe_u32 v5, v2, 1, 7
	v_cmp_lt_u32_e64 s[36:37], s6, v2
	v_lshlrev_b32_e32 v160, 2, v6
	v_lshlrev_b32_e32 v7, 1, v2
	s_movk_i32 s6, 0xfe00
	v_mad_u32_u24 v45, v6, s7, 0
	v_lshl_add_u64 v[0:1], s[34:35], 0, v[160:161]
	v_and_or_b32 v46, v7, s6, v5
	v_lshlrev_b32_e32 v47, 2, v44
	v_and_b32_e32 v48, -2, v2
	v_lshl_add_u32 v49, v44, 1, v44
	v_lshlrev_b32_e32 v160, 2, v4
	v_lshlrev_b32_e32 v2, 1, v6
	v_add_u32_e32 v50, 64, v3
	v_xor_b32_e32 v25, 0x80000000, v25
	v_mov_b32_e32 v56, 0x200
	v_cndmask_b32_e64 v56, 0, v56, s[36:37]
	v_and_b32_e32 v67, 15, v214
	v_bfe_u32 v68, v214, 4, 2
	v_lshrrev_b32_e32 v69, 6, v214
	v_mul_u32_u24_e32 v57, 0x204, v67
	v_lshl_add_u32 v57, v68, 2, v57
	v_lshlrev_b32_e32 v66, 3, v68
	v_lshl_add_u32 v70, v69, 5, v67
	v_and_b32_e32 v58, 0x7f, v70
	v_add_u32_e32 v71, 16, v70
	v_and_b32_e32 v59, 0x7f, v71
	v_and_b32_e32 v62, 0x80, v70
	v_lshl_add_u32 v62, v62, 2, v58
	v_and_b32_e32 v63, 0x80, v71
	v_lshl_add_u32 v63, v63, 2, v59
	v_mul_u32_u24_e32 v60, v68, v58
	v_and_b32_e32 v60, 0x7f, v60
	v_mul_u32_u24_e32 v61, v68, v59
	v_and_b32_e32 v61, 0x7f, v61
	v_lshlrev_b32_e32 v58, 2, v58
	v_and_b32_e32 v58, 0x7f, v58
	v_lshlrev_b32_e32 v59, 2, v59
	v_and_b32_e32 v59, 0x7f, v59
	v_lshlrev_b32_e32 v64, 4, v68
	v_mov_b32_e32 v65, 0
	v_lshl_add_u64 v[64:65], s[34:35], 0, v[64:65]
	v_mov_b32_e32 v67, 0
	v_readlane_b32 s6, v254, 22
	s_branch .LBB0_59
.LBB0_58:
	s_mov_b32 s12, 0x3db504f3
	s_lshl_b32 s20, s7, 2
	v_lshl_add_u64 v[32:33], v[64:65], 0, s[20:21]
	global_load_dwordx4 v[88:91], v[32:33], off
	v_add_u32_e32 v40, s44, v62
	v_add_u32_e32 v42, s44, v63
	v_mov_b32_e32 v41, 0
	v_mov_b32_e32 v43, 0
	v_lshlrev_b64 v[40:41], 11, v[40:41]
	v_lshlrev_b64 v[42:43], 11, v[42:43]
	s_nop 3
	v_pk_mul_f32 v[4:5], v[4:5], s[12:13] op_sel_hi:[1,0]
	v_pk_mul_f32 v[6:7], v[6:7], s[12:13] op_sel_hi:[1,0]
	v_pk_mul_f32 v[8:9], v[8:9], s[12:13] op_sel_hi:[1,0]
	v_pk_mul_f32 v[10:11], v[10:11], s[12:13] op_sel_hi:[1,0]
	v_readlane_b32 s12, v252, 19
	v_readlane_b32 s13, v252, 20
	s_lshl_b32 s20, s7, 1
	v_lshl_add_u64 v[40:41], s[12:13], 0, v[40:41]
	v_lshl_add_u64 v[42:43], s[12:13], 0, v[42:43]
	v_lshl_add_u64 v[40:41], v[40:41], 0, s[20:21]
	v_lshl_add_u64 v[42:43], v[42:43], 0, s[20:21]
	v_lshl_add_u64 v[40:41], v[40:41], 0, v[66:67]
	v_lshl_add_u64 v[42:43], v[42:43], 0, v[66:67]
	s_add_i32 s6, s6, s90
	s_cmpk_gt_i32 s6, 0xff
	s_waitcnt vmcnt(0)
	v_pk_mul_f32 v[4:5], v[4:5], v[88:89]
	v_pk_mul_f32 v[6:7], v[6:7], v[90:91]
	v_pk_mul_f32 v[8:9], v[8:9], v[88:89]
	v_pk_mul_f32 v[10:11], v[10:11], v[90:91]
	v_cvt_pk_bf16_f32 v4, v4, v5
	v_cvt_pk_bf16_f32 v5, v6, v7
	v_cvt_pk_bf16_f32 v8, v8, v9
	v_cvt_pk_bf16_f32 v9, v10, v11
	global_store_dwordx2 v[40:41], v[4:5], off
	global_store_dwordx2 v[42:43], v[8:9], off
	s_barrier
	s_cbranch_scc1 .LBB0_79

; __device__ void prep_zfold(const float* __restrict__ wmix  , const float* __restrict__ gain, bf16_t* __restrict__ WM1, int& tbase, float* lt) {
;     ...
;       for (int c = 0; c < 128; ++c) {
;         const int idx = (c * cc) & 127; const float w = ri ? -sinT[idx] : cosT[idx];
;         a0 += lp[c] * w; a1 += lp[129 + c] * w; a2 += lp[2 * 129 + c] * w; a3 += lp[3 * 129 + c] * w;
;         a4 += lp[4 * 129 + c] * w; a5 += lp[5 * 129 + c] * w; a6 += lp[6 * 129 + c] * w; a7 += lp[7 * 129 + c] * w;
;       }
.Lzf_entry:
	v_mov_b32_e32 v20, v60
	v_mov_b32_e32 v21, v61
	v_mov_b32_e32 v22, v57
.Lzf_loop:
	ds_read_b32 v16, v22 offset:0
	v_lshl_add_u32 v80, v20, 2, v56
	ds_read_b32 v72, v80 offset:8256
	v_lshl_add_u32 v81, v21, 2, v56
	ds_read_b32 v76, v81 offset:8256
	v_add_u32_e32 v20, v20, v58
	v_and_b32_e32 v20, 0x7f, v20
	v_add_u32_e32 v21, v21, v59
	v_and_b32_e32 v21, 0x7f, v21
	ds_read_b32 v17, v22 offset:16
	v_lshl_add_u32 v82, v20, 2, v56
	ds_read_b32 v73, v82 offset:8256
	v_lshl_add_u32 v83, v21, 2, v56
	ds_read_b32 v77, v83 offset:8256
	v_add_u32_e32 v20, v20, v58
	v_and_b32_e32 v20, 0x7f, v20
	v_add_u32_e32 v21, v21, v59
	v_and_b32_e32 v21, 0x7f, v21
	ds_read_b32 v18, v22 offset:32
	v_lshl_add_u32 v84, v20, 2, v56
	ds_read_b32 v74, v84 offset:8256
	v_lshl_add_u32 v85, v21, 2, v56
	ds_read_b32 v78, v85 offset:8256
	v_add_u32_e32 v20, v20, v58
	v_and_b32_e32 v20, 0x7f, v20
	v_add_u32_e32 v21, v21, v59
	v_and_b32_e32 v21, 0x7f, v21
	ds_read_b32 v19, v22 offset:48
	v_lshl_add_u32 v86, v20, 2, v56
	ds_read_b32 v75, v86 offset:8256
	v_lshl_add_u32 v87, v21, 2, v56
	ds_read_b32 v79, v87 offset:8256
	v_add_u32_e32 v20, v20, v58
	v_and_b32_e32 v20, 0x7f, v20
	v_add_u32_e32 v21, v21, v59
	v_and_b32_e32 v21, 0x7f, v21
	v_add_u32_e32 v22, 64, v22
	s_add_i32 s12, s12, 1
	s_waitcnt lgkmcnt(10)
	v_mfma_f32_16x16x4_f32 v[4:7], v16, v72, v[4:7]
	s_waitcnt lgkmcnt(9)
	v_mfma_f32_16x16x4_f32 v[8:11], v16, v76, v[8:11]
	s_waitcnt lgkmcnt(7)
	v_mfma_f32_16x16x4_f32 v[4:7], v17, v73, v[4:7]
	s_waitcnt lgkmcnt(6)
	v_mfma_f32_16x16x4_f32 v[8:11], v17, v77, v[8:11]
	s_waitcnt lgkmcnt(4)
	v_mfma_f32_16x16x4_f32 v[4:7], v18, v74, v[4:7]
	s_waitcnt lgkmcnt(3)
	v_mfma_f32_16x16x4_f32 v[8:11], v18, v78, v[8:11]
	s_waitcnt lgkmcnt(1)
	v_mfma_f32_16x16x4_f32 v[4:7], v19, v75, v[4:7]
	s_waitcnt lgkmcnt(0)
	v_mfma_f32_16x16x4_f32 v[8:11], v19, v79, v[8:11]
	s_cmp_eq_u32 s12, 8
	s_cbranch_scc0 .Lzf_loop
	s_branch .LBB0_58
